# grid barrier release: non-leader workgroups poll the cross-XCD arrival counter directly instead of their XCD's release word (one hop less); 9 of 10 barrier instances
# speedup vs baseline: 1.0011x; 1.0011x over previous
; __device__ __forceinline__ unsigned xb_ld(unsigned* p)              { return __hip_atomic_load(p, __ATOMIC_RELAXED, __HIP_MEMORY_SCOPE_AGENT); }
; __device__ __forceinline__ unsigned xb_add(unsigned* p, unsigned v) { return __hip_atomic_fetch_add(p, v, __ATOMIC_RELAXED, __HIP_MEMORY_SCOPE_AGENT); }
; #define XB_SPIN(cond, bar) do { unsigned _sp = 0; while (cond) { __builtin_amdgcn_s_sleep(1); \
;     if ((++_sp & 255u) == 0u) { if (xb_ld(&(bar)[XB_TMO])) break; if (_sp > XB_SPIN_CAP) { atomicAdd(&(bar)[XB_TMO], 1u); break; } } } } while (0)
; __device__ __forceinline__ void xcd_barrier(const XcdBarrier& b) {
;     ...
;         const unsigned old = xb_add(&bar[XB_XSUB(b.x)], 1u);
;         const unsigned gen = old / nloc;
;         if (old + 1u == (gen + 1u) * nloc) {
;             __builtin_amdgcn_fence(__ATOMIC_RELEASE, "agent");
;             asm volatile("s_waitcnt vmcnt(0)" ::: "memory");
;             const unsigned og = xb_add(&bar[XB_TOP], 1u);
;             const unsigned tg = og / nx;
;             if (og + 1u == (tg + 1u) * nx) xb_add(&bar[XB_TOPGEN], 1u);
;             else XB_SPIN(xb_ld(&bar[XB_TOPGEN]) == tg, bar);
;             __builtin_amdgcn_fence(__ATOMIC_ACQUIRE, "agent");
;             xb_add(&bar[XB_XGEN(b.x)], 1u);
;             asm volatile("s_waitcnt vmcnt(0)" ::: "memory");
;         } else {
;             XB_SPIN(xb_ld(&bar[XB_XGEN(b.x)]) == gen, bar);
.LBB0_354:
	s_or_b64 exec, exec, s[8:9]
	v_cvt_f32_u32_e32 v5, v3
	s_waitcnt vmcnt(0)
	v_readfirstlane_b32 s6, v4
	v_sub_u32_e32 v4, 0, v3
	v_rcp_iflag_f32_e32 v5, v5
	v_add_u32_e32 v6, s6, v1
	v_mul_f32_e32 v5, 0x4f7ffffe, v5
	v_cvt_u32_f32_e32 v5, v5
	v_mul_lo_u32 v1, v4, v5
	v_mul_hi_u32 v1, v5, v1
	v_add_u32_e32 v1, v5, v1
	v_mul_hi_u32 v1, v6, v1
	v_mul_lo_u32 v4, v1, v3
	v_sub_u32_e32 v4, v6, v4
	v_add_u32_e32 v5, 1, v1
	v_cmp_ge_u32_e32 vcc, v4, v3
	s_nop 1
	v_cndmask_b32_e32 v1, v1, v5, vcc
	v_sub_u32_e32 v5, v4, v3
	v_cndmask_b32_e32 v4, v4, v5, vcc
	v_add_u32_e32 v5, 1, v1
	v_cmp_ge_u32_e32 vcc, v4, v3
	v_add_u32_e32 v4, 1, v6
	s_nop 0
	v_cndmask_b32_e32 v1, v1, v5, vcc
	v_mul_lo_u32 v5, v3, v1
	v_add_u32_e32 v3, v5, v3
	v_cmp_ne_u32_e32 vcc, v4, v3
	s_and_saveexec_b64 s[6:7], vcc
	s_xor_b64 s[6:7], exec, s[6:7]
	s_cbranch_execz .LBB0_368
	s_movk_i32 s56, 0xd00
	s_lshl_b64 s[8:9], s[56:57], 2
	v_readlane_b32 s10, v252, 26
	v_readlane_b32 s11, v252, 27
	s_add_u32 s16, s10, s8
	s_addc_u32 s17, s11, s9
	s_waitcnt lgkmcnt(0)
	v_add_u32_e32 v28, 1, v1
	v_mul_lo_u32 v28, v28, v2
	global_load_dword v2, v33, s[16:17] sc1
	s_waitcnt vmcnt(0)
	v_cmp_lt_u32_e32 vcc, v2, v28
	s_and_saveexec_b64 s[8:9], vcc
	s_cbranch_execz .LBB0_367
	s_mov_b32 s38, 1
	s_mov_b64 s[18:19], 0
	s_branch .LBB0_358

; __device__ __forceinline__ unsigned xb_ld(unsigned* p)              { return __hip_atomic_load(p, __ATOMIC_RELAXED, __HIP_MEMORY_SCOPE_AGENT); }
; #define XB_SPIN(cond, bar) do { unsigned _sp = 0; while (cond) { __builtin_amdgcn_s_sleep(1); \
;     if ((++_sp & 255u) == 0u) { if (xb_ld(&(bar)[XB_TMO])) break; if (_sp > XB_SPIN_CAP) { atomicAdd(&(bar)[XB_TMO], 1u); break; } } } } while (0)
; __device__ __forceinline__ void xcd_barrier(const XcdBarrier& b) {
;     ...
;         } else {
;             XB_SPIN(xb_ld(&bar[XB_XGEN(b.x)]) == gen, bar);
.LBB0_360:
	global_load_dword v2, v33, s[16:17] sc1
	s_add_i32 s38, s38, 1
	s_mov_b64 s[28:29], -1
	s_waitcnt vmcnt(0)
	v_cmp_ge_u32_e32 vcc, v2, v28
	s_orn2_b64 s[26:27], vcc, exec
	s_branch .LBB0_357

; __device__ __forceinline__ unsigned xb_ld(unsigned* p)              { return __hip_atomic_load(p, __ATOMIC_RELAXED, __HIP_MEMORY_SCOPE_AGENT); }
; __device__ __forceinline__ unsigned xb_add(unsigned* p, unsigned v) { return __hip_atomic_fetch_add(p, v, __ATOMIC_RELAXED, __HIP_MEMORY_SCOPE_AGENT); }
; #define XB_SPIN(cond, bar) do { unsigned _sp = 0; while (cond) { __builtin_amdgcn_s_sleep(1); \
;     if ((++_sp & 255u) == 0u) { if (xb_ld(&(bar)[XB_TMO])) break; if (_sp > XB_SPIN_CAP) { atomicAdd(&(bar)[XB_TMO], 1u); break; } } } } while (0)
; __device__ __forceinline__ void xcd_barrier(const XcdBarrier& b) {
;     ...
;         const unsigned old = xb_add(&bar[XB_XSUB(b.x)], 1u);
;         const unsigned gen = old / nloc;
;         if (old + 1u == (gen + 1u) * nloc) {
;             __builtin_amdgcn_fence(__ATOMIC_RELEASE, "agent");
;             asm volatile("s_waitcnt vmcnt(0)" ::: "memory");
;             const unsigned og = xb_add(&bar[XB_TOP], 1u);
;             const unsigned tg = og / nx;
;             if (og + 1u == (tg + 1u) * nx) xb_add(&bar[XB_TOPGEN], 1u);
;             else XB_SPIN(xb_ld(&bar[XB_TOPGEN]) == tg, bar);
;             __builtin_amdgcn_fence(__ATOMIC_ACQUIRE, "agent");
;             xb_add(&bar[XB_XGEN(b.x)], 1u);
;             asm volatile("s_waitcnt vmcnt(0)" ::: "memory");
;         } else {
;             XB_SPIN(xb_ld(&bar[XB_XGEN(b.x)]) == gen, bar);
.LBB0_500:
	s_or_b64 exec, exec, s[6:7]
	v_cvt_f32_u32_e32 v5, v3
	s_waitcnt vmcnt(0)
	v_readfirstlane_b32 s4, v4
	v_sub_u32_e32 v4, 0, v3
	v_rcp_iflag_f32_e32 v5, v5
	v_add_u32_e32 v6, s4, v1
	v_mul_f32_e32 v5, 0x4f7ffffe, v5
	v_cvt_u32_f32_e32 v5, v5
	v_mul_lo_u32 v1, v4, v5
	v_mul_hi_u32 v1, v5, v1
	v_add_u32_e32 v1, v5, v1
	v_mul_hi_u32 v1, v6, v1
	v_mul_lo_u32 v4, v1, v3
	v_sub_u32_e32 v4, v6, v4
	v_add_u32_e32 v5, 1, v1
	v_cmp_ge_u32_e32 vcc, v4, v3
	s_nop 1
	v_cndmask_b32_e32 v1, v1, v5, vcc
	v_sub_u32_e32 v5, v4, v3
	v_cndmask_b32_e32 v4, v4, v5, vcc
	v_add_u32_e32 v5, 1, v1
	v_cmp_ge_u32_e32 vcc, v4, v3
	v_add_u32_e32 v4, 1, v6
	s_nop 0
	v_cndmask_b32_e32 v1, v1, v5, vcc
	v_mul_lo_u32 v5, v3, v1
	v_add_u32_e32 v3, v5, v3
	v_cmp_ne_u32_e32 vcc, v4, v3
	s_and_saveexec_b64 s[4:5], vcc
	s_xor_b64 s[4:5], exec, s[4:5]
	s_cbranch_execz .LBB0_514
	s_movk_i32 s56, 0xd00
	s_lshl_b64 s[6:7], s[56:57], 2
	v_readlane_b32 s8, v252, 26
	v_readlane_b32 s9, v252, 27
	s_add_u32 s8, s8, s6
	s_addc_u32 s9, s9, s7
	s_waitcnt lgkmcnt(0)
	v_add_u32_e32 v28, 1, v1
	v_mul_lo_u32 v28, v28, v2
	s_nop 1
	global_load_dword v2, v33, s[8:9] sc1
	s_waitcnt vmcnt(0)
	v_cmp_lt_u32_e32 vcc, v2, v28
	s_and_saveexec_b64 s[6:7], vcc
	s_cbranch_execz .LBB0_513
	s_mov_b32 s25, 1
	s_mov_b64 s[10:11], 0
	s_branch .LBB0_504

; __device__ __forceinline__ unsigned xb_ld(unsigned* p)              { return __hip_atomic_load(p, __ATOMIC_RELAXED, __HIP_MEMORY_SCOPE_AGENT); }
; #define XB_SPIN(cond, bar) do { unsigned _sp = 0; while (cond) { __builtin_amdgcn_s_sleep(1); \
;     if ((++_sp & 255u) == 0u) { if (xb_ld(&(bar)[XB_TMO])) break; if (_sp > XB_SPIN_CAP) { atomicAdd(&(bar)[XB_TMO], 1u); break; } } } } while (0)
; __device__ __forceinline__ void xcd_barrier(const XcdBarrier& b) {
;     ...
;         } else {
;             XB_SPIN(xb_ld(&bar[XB_XGEN(b.x)]) == gen, bar);
.LBB0_506:
	global_load_dword v2, v33, s[8:9] sc1
	s_add_i32 s25, s25, 1
	s_mov_b64 s[16:17], -1
	s_waitcnt vmcnt(0)
	v_cmp_ge_u32_e32 vcc, v2, v28
	s_orn2_b64 s[14:15], vcc, exec
	s_branch .LBB0_503

; __device__ __forceinline__ unsigned xb_ld(unsigned* p)              { return __hip_atomic_load(p, __ATOMIC_RELAXED, __HIP_MEMORY_SCOPE_AGENT); }
; __device__ __forceinline__ unsigned xb_add(unsigned* p, unsigned v) { return __hip_atomic_fetch_add(p, v, __ATOMIC_RELAXED, __HIP_MEMORY_SCOPE_AGENT); }
; #define XB_SPIN(cond, bar) do { unsigned _sp = 0; while (cond) { __builtin_amdgcn_s_sleep(1); \
;     if ((++_sp & 255u) == 0u) { if (xb_ld(&(bar)[XB_TMO])) break; if (_sp > XB_SPIN_CAP) { atomicAdd(&(bar)[XB_TMO], 1u); break; } } } } while (0)
; __device__ __forceinline__ void xcd_barrier(const XcdBarrier& b) {
;     ...
;         const unsigned old = xb_add(&bar[XB_XSUB(b.x)], 1u);
;         const unsigned gen = old / nloc;
;         if (old + 1u == (gen + 1u) * nloc) {
;             __builtin_amdgcn_fence(__ATOMIC_RELEASE, "agent");
;             asm volatile("s_waitcnt vmcnt(0)" ::: "memory");
;             const unsigned og = xb_add(&bar[XB_TOP], 1u);
;             const unsigned tg = og / nx;
;             if (og + 1u == (tg + 1u) * nx) xb_add(&bar[XB_TOPGEN], 1u);
;             else XB_SPIN(xb_ld(&bar[XB_TOPGEN]) == tg, bar);
;             __builtin_amdgcn_fence(__ATOMIC_ACQUIRE, "agent");
;             xb_add(&bar[XB_XGEN(b.x)], 1u);
;             asm volatile("s_waitcnt vmcnt(0)" ::: "memory");
;         } else {
;             XB_SPIN(xb_ld(&bar[XB_XGEN(b.x)]) == gen, bar);
.LBB0_791:
	s_or_b64 exec, exec, s[6:7]
	v_cvt_f32_u32_e32 v5, v3
	s_waitcnt vmcnt(0)
	v_readfirstlane_b32 s4, v4
	v_sub_u32_e32 v4, 0, v3
	v_rcp_iflag_f32_e32 v5, v5
	v_add_u32_e32 v6, s4, v1
	v_mul_f32_e32 v5, 0x4f7ffffe, v5
	v_cvt_u32_f32_e32 v5, v5
	v_mul_lo_u32 v1, v4, v5
	v_mul_hi_u32 v1, v5, v1
	v_add_u32_e32 v1, v5, v1
	v_mul_hi_u32 v1, v6, v1
	v_mul_lo_u32 v4, v1, v3
	v_sub_u32_e32 v4, v6, v4
	v_add_u32_e32 v5, 1, v1
	v_cmp_ge_u32_e32 vcc, v4, v3
	s_nop 1
	v_cndmask_b32_e32 v1, v1, v5, vcc
	v_sub_u32_e32 v5, v4, v3
	v_cndmask_b32_e32 v4, v4, v5, vcc
	v_add_u32_e32 v5, 1, v1
	v_cmp_ge_u32_e32 vcc, v4, v3
	v_add_u32_e32 v4, 1, v6
	s_nop 0
	v_cndmask_b32_e32 v1, v1, v5, vcc
	v_mul_lo_u32 v5, v3, v1
	v_add_u32_e32 v3, v5, v3
	v_cmp_ne_u32_e32 vcc, v4, v3
	s_and_saveexec_b64 s[4:5], vcc
	s_xor_b64 s[4:5], exec, s[4:5]
	s_cbranch_execz .LBB0_805
	s_movk_i32 s56, 0xd00
	s_lshl_b64 s[6:7], s[56:57], 2
	v_readlane_b32 s8, v252, 26
	v_readlane_b32 s9, v252, 27
	s_add_u32 s8, s8, s6
	s_addc_u32 s9, s9, s7
	s_waitcnt lgkmcnt(0)
	v_add_u32_e32 v28, 1, v1
	v_mul_lo_u32 v28, v28, v2
	s_nop 1
	global_load_dword v2, v33, s[8:9] sc1
	s_waitcnt vmcnt(0)
	v_cmp_lt_u32_e32 vcc, v2, v28
	s_and_saveexec_b64 s[6:7], vcc
	s_cbranch_execz .LBB0_804
	s_mov_b32 s23, 1
	s_mov_b64 s[10:11], 0
	s_branch .LBB0_795

; __device__ __forceinline__ unsigned xb_ld(unsigned* p)              { return __hip_atomic_load(p, __ATOMIC_RELAXED, __HIP_MEMORY_SCOPE_AGENT); }
; #define XB_SPIN(cond, bar) do { unsigned _sp = 0; while (cond) { __builtin_amdgcn_s_sleep(1); \
;     if ((++_sp & 255u) == 0u) { if (xb_ld(&(bar)[XB_TMO])) break; if (_sp > XB_SPIN_CAP) { atomicAdd(&(bar)[XB_TMO], 1u); break; } } } } while (0)
; __device__ __forceinline__ void xcd_barrier(const XcdBarrier& b) {
;     ...
;         } else {
;             XB_SPIN(xb_ld(&bar[XB_XGEN(b.x)]) == gen, bar);
.LBB0_797:
	global_load_dword v2, v33, s[8:9] sc1
	s_add_i32 s23, s23, 1
	s_mov_b64 s[16:17], -1
	s_waitcnt vmcnt(0)
	v_cmp_ge_u32_e32 vcc, v2, v28
	s_orn2_b64 s[14:15], vcc, exec
	s_branch .LBB0_794

; __device__ __forceinline__ unsigned xb_ld(unsigned* p)              { return __hip_atomic_load(p, __ATOMIC_RELAXED, __HIP_MEMORY_SCOPE_AGENT); }
; __device__ __forceinline__ unsigned xb_add(unsigned* p, unsigned v) { return __hip_atomic_fetch_add(p, v, __ATOMIC_RELAXED, __HIP_MEMORY_SCOPE_AGENT); }
; #define XB_SPIN(cond, bar) do { unsigned _sp = 0; while (cond) { __builtin_amdgcn_s_sleep(1); \
;     if ((++_sp & 255u) == 0u) { if (xb_ld(&(bar)[XB_TMO])) break; if (_sp > XB_SPIN_CAP) { atomicAdd(&(bar)[XB_TMO], 1u); break; } } } } while (0)
; __device__ __forceinline__ void xcd_barrier(const XcdBarrier& b) {
;     ...
;         const unsigned old = xb_add(&bar[XB_XSUB(b.x)], 1u);
;         const unsigned gen = old / nloc;
;         if (old + 1u == (gen + 1u) * nloc) {
;             __builtin_amdgcn_fence(__ATOMIC_RELEASE, "agent");
;             asm volatile("s_waitcnt vmcnt(0)" ::: "memory");
;             const unsigned og = xb_add(&bar[XB_TOP], 1u);
;             const unsigned tg = og / nx;
;             if (og + 1u == (tg + 1u) * nx) xb_add(&bar[XB_TOPGEN], 1u);
;             else XB_SPIN(xb_ld(&bar[XB_TOPGEN]) == tg, bar);
;             __builtin_amdgcn_fence(__ATOMIC_ACQUIRE, "agent");
;             xb_add(&bar[XB_XGEN(b.x)], 1u);
;             asm volatile("s_waitcnt vmcnt(0)" ::: "memory");
;         } else {
;             XB_SPIN(xb_ld(&bar[XB_XGEN(b.x)]) == gen, bar);
.LBB0_1210:
	s_or_b64 exec, exec, s[8:9]
	v_cvt_f32_u32_e32 v5, v3
	s_waitcnt vmcnt(0)
	v_readfirstlane_b32 s3, v4
	v_sub_u32_e32 v4, 0, v3
	v_rcp_iflag_f32_e32 v5, v5
	v_add_u32_e32 v6, s3, v1
	v_mul_f32_e32 v5, 0x4f7ffffe, v5
	v_cvt_u32_f32_e32 v5, v5
	v_mul_lo_u32 v1, v4, v5
	v_mul_hi_u32 v1, v5, v1
	v_add_u32_e32 v1, v5, v1
	v_mul_hi_u32 v1, v6, v1
	v_mul_lo_u32 v4, v1, v3
	v_sub_u32_e32 v4, v6, v4
	v_add_u32_e32 v5, 1, v1
	v_cmp_ge_u32_e32 vcc, v4, v3
	s_nop 1
	v_cndmask_b32_e32 v1, v1, v5, vcc
	v_sub_u32_e32 v5, v4, v3
	v_cndmask_b32_e32 v4, v4, v5, vcc
	v_add_u32_e32 v5, 1, v1
	v_cmp_ge_u32_e32 vcc, v4, v3
	v_add_u32_e32 v4, 1, v6
	s_nop 0
	v_cndmask_b32_e32 v1, v1, v5, vcc
	v_mul_lo_u32 v5, v3, v1
	v_add_u32_e32 v3, v5, v3
	v_cmp_ne_u32_e32 vcc, v4, v3
	s_and_saveexec_b64 s[6:7], vcc
	s_xor_b64 s[6:7], exec, s[6:7]
	s_cbranch_execz .LBB0_1224
	s_movk_i32 s56, 0xd00
	s_lshl_b64 s[8:9], s[56:57], 2
	v_readlane_b32 s12, v252, 26
	v_readlane_b32 s13, v252, 27
	s_add_u32 s12, s12, s8
	s_addc_u32 s13, s13, s9
	s_waitcnt lgkmcnt(0)
	v_add_u32_e32 v28, 1, v1
	v_mul_lo_u32 v28, v28, v2
	s_nop 1
	global_load_dword v2, v33, s[12:13] sc1
	s_waitcnt vmcnt(0)
	v_cmp_lt_u32_e32 vcc, v2, v28
	s_and_saveexec_b64 s[8:9], vcc
	s_cbranch_execz .LBB0_1223
	s_mov_b32 s3, 1
	s_mov_b64 s[14:15], 0
	s_branch .LBB0_1214

; __device__ __forceinline__ unsigned xb_ld(unsigned* p)              { return __hip_atomic_load(p, __ATOMIC_RELAXED, __HIP_MEMORY_SCOPE_AGENT); }
; #define XB_SPIN(cond, bar) do { unsigned _sp = 0; while (cond) { __builtin_amdgcn_s_sleep(1); \
;     if ((++_sp & 255u) == 0u) { if (xb_ld(&(bar)[XB_TMO])) break; if (_sp > XB_SPIN_CAP) { atomicAdd(&(bar)[XB_TMO], 1u); break; } } } } while (0)
; __device__ __forceinline__ void xcd_barrier(const XcdBarrier& b) {
;     ...
;         } else {
;             XB_SPIN(xb_ld(&bar[XB_XGEN(b.x)]) == gen, bar);
.LBB0_1216:
	global_load_dword v2, v33, s[12:13] sc1
	s_add_i32 s3, s3, 1
	s_mov_b64 s[22:23], -1
	s_waitcnt vmcnt(0)
	v_cmp_ge_u32_e32 vcc, v2, v28
	s_orn2_b64 s[18:19], vcc, exec
	s_branch .LBB0_1213

; __device__ __forceinline__ unsigned xb_ld(unsigned* p)              { return __hip_atomic_load(p, __ATOMIC_RELAXED, __HIP_MEMORY_SCOPE_AGENT); }
; __device__ __forceinline__ unsigned xb_add(unsigned* p, unsigned v) { return __hip_atomic_fetch_add(p, v, __ATOMIC_RELAXED, __HIP_MEMORY_SCOPE_AGENT); }
; #define XB_SPIN(cond, bar) do { unsigned _sp = 0; while (cond) { __builtin_amdgcn_s_sleep(1); \
;     if ((++_sp & 255u) == 0u) { if (xb_ld(&(bar)[XB_TMO])) break; if (_sp > XB_SPIN_CAP) { atomicAdd(&(bar)[XB_TMO], 1u); break; } } } } while (0)
; __device__ __forceinline__ void xcd_barrier(const XcdBarrier& b) {
;     ...
;         const unsigned old = xb_add(&bar[XB_XSUB(b.x)], 1u);
;         const unsigned gen = old / nloc;
;         if (old + 1u == (gen + 1u) * nloc) {
;             __builtin_amdgcn_fence(__ATOMIC_RELEASE, "agent");
;             asm volatile("s_waitcnt vmcnt(0)" ::: "memory");
;             const unsigned og = xb_add(&bar[XB_TOP], 1u);
;             const unsigned tg = og / nx;
;             if (og + 1u == (tg + 1u) * nx) xb_add(&bar[XB_TOPGEN], 1u);
;             else XB_SPIN(xb_ld(&bar[XB_TOPGEN]) == tg, bar);
;             __builtin_amdgcn_fence(__ATOMIC_ACQUIRE, "agent");
;             xb_add(&bar[XB_XGEN(b.x)], 1u);
;             asm volatile("s_waitcnt vmcnt(0)" ::: "memory");
;         } else {
;             XB_SPIN(xb_ld(&bar[XB_XGEN(b.x)]) == gen, bar);
.LBB0_1271:
	s_or_b64 exec, exec, s[8:9]
	v_cvt_f32_u32_e32 v5, v3
	s_waitcnt vmcnt(0)
	v_readfirstlane_b32 s3, v4
	v_sub_u32_e32 v4, 0, v3
	v_rcp_iflag_f32_e32 v5, v5
	v_add_u32_e32 v6, s3, v1
	v_mul_f32_e32 v5, 0x4f7ffffe, v5
	v_cvt_u32_f32_e32 v5, v5
	v_mul_lo_u32 v1, v4, v5
	v_mul_hi_u32 v1, v5, v1
	v_add_u32_e32 v1, v5, v1
	v_mul_hi_u32 v1, v6, v1
	v_mul_lo_u32 v4, v1, v3
	v_sub_u32_e32 v4, v6, v4
	v_add_u32_e32 v5, 1, v1
	v_cmp_ge_u32_e32 vcc, v4, v3
	s_nop 1
	v_cndmask_b32_e32 v1, v1, v5, vcc
	v_sub_u32_e32 v5, v4, v3
	v_cndmask_b32_e32 v4, v4, v5, vcc
	v_add_u32_e32 v5, 1, v1
	v_cmp_ge_u32_e32 vcc, v4, v3
	v_add_u32_e32 v4, 1, v6
	s_nop 0
	v_cndmask_b32_e32 v1, v1, v5, vcc
	v_mul_lo_u32 v5, v3, v1
	v_add_u32_e32 v3, v5, v3
	v_cmp_ne_u32_e32 vcc, v4, v3
	s_and_saveexec_b64 s[6:7], vcc
	s_xor_b64 s[6:7], exec, s[6:7]
	s_cbranch_execz .LBB0_1285
	s_movk_i32 s56, 0xd00
	s_lshl_b64 s[8:9], s[56:57], 2
	v_readlane_b32 s10, v252, 26
	v_readlane_b32 s11, v252, 27
	s_add_u32 s10, s10, s8
	s_addc_u32 s11, s11, s9
	s_waitcnt lgkmcnt(0)
	v_add_u32_e32 v28, 1, v1
	v_mul_lo_u32 v28, v28, v2
	s_nop 1
	global_load_dword v2, v33, s[10:11] sc1
	s_waitcnt vmcnt(0)
	v_cmp_lt_u32_e32 vcc, v2, v28
	s_and_saveexec_b64 s[8:9], vcc
	s_cbranch_execz .LBB0_1284
	s_mov_b32 s3, 1
	s_mov_b64 s[12:13], 0
	s_branch .LBB0_1275

; __device__ __forceinline__ unsigned xb_ld(unsigned* p)              { return __hip_atomic_load(p, __ATOMIC_RELAXED, __HIP_MEMORY_SCOPE_AGENT); }
; #define XB_SPIN(cond, bar) do { unsigned _sp = 0; while (cond) { __builtin_amdgcn_s_sleep(1); \
;     if ((++_sp & 255u) == 0u) { if (xb_ld(&(bar)[XB_TMO])) break; if (_sp > XB_SPIN_CAP) { atomicAdd(&(bar)[XB_TMO], 1u); break; } } } } while (0)
; __device__ __forceinline__ void xcd_barrier(const XcdBarrier& b) {
;     ...
;         } else {
;             XB_SPIN(xb_ld(&bar[XB_XGEN(b.x)]) == gen, bar);
.LBB0_1277:
	global_load_dword v2, v33, s[10:11] sc1
	s_add_i32 s3, s3, 1
	s_mov_b64 s[18:19], -1
	s_waitcnt vmcnt(0)
	v_cmp_ge_u32_e32 vcc, v2, v28
	s_orn2_b64 s[16:17], vcc, exec
	s_branch .LBB0_1274
